# attention output stores written through (sc1) so the grid barrier's L2 write-back that follows has less left to do
# speedup vs baseline: 1.0015x; 1.0009x over previous
; __device__ __forceinline__ int crow(int r,int hi){return (r&3)+8*(r>>2)+4*hi;}
; __device__ __forceinline__ unsigned cvtpk_s(float lo,float hi){f32x2_t v={lo,hi};bf16x2_t b=__builtin_convertvector(v,bf16x2_t);return __builtin_bit_cast(unsigned,b);}
; #define ATTN_STORE16(p,v) st16_wt((p),(v))
;     ...
;   {auto rr=__builtin_amdgcn_permlane32_swap(__float_as_uint(l_reg),__float_as_uint(l_reg),false,false);l_reg=__uint_as_float(rr[0])+__uint_as_float(rr[1]);}
;   if(hi==0)wsf[32+r32]=l_reg;asm volatile("s_waitcnt lgkmcnt(0)":::"memory");
;   float rli[16];
;   #pragma unroll
;   for(int r=0;r<16;++r)rli[r]=__builtin_amdgcn_rcpf(wsf[32+crow(r,hi)]);
;   bf16*Ow=Ob+(long)(wid*QBLK)*OP;
;   { bf16*stg=(bf16*)(shm+LDS_OST+wid*MWAVE);
;     bf16*stl=stg+bsel*2048+hi*256+r32;
;     if(emode>=2){
;       #pragma unroll
;       for(int r=0;r<16;++r){
;         #pragma unroll
;         for(int d0=0;d0<2;++d0){ const float old=__uint_as_float((unsigned)stl[cr0(r)*64+d0*32]<<16); stl[cr0(r)*64+d0*32]=(bf16)(cvtpk_s(old-lam*(o[d0][r]*rli[r]),0.f)&0xffffu);} }
;     } else {
;       #pragma unroll
;       for(int r=0;r<16;++r){
;         #pragma unroll
;         for(int d0=0;d0<2;++d0)stl[cr0(r)*64+d0*32]=(bf16)(cvtpk_s(o[d0][r]*rli[r],0.f)&0xffffu);}
;     }
;     asm volatile("s_waitcnt lgkmcnt(0)":::"memory");
;     if(emode==0){
;       #pragma unroll
;       for(int i=0;i<4;++i){const int row=i*8+(lane>>3),ch=lane&7; const u32x4 v=*(const u32x4*)(stg+row*64+ch*8); ATTN_STORE16(Ow+(long)row*OP+ch*8,v);}
.LBB0_1378:
	s_or_b64 exec, exec, s[0:1]
	s_waitcnt lgkmcnt(0)
	ds_read_b128 v[2:5], v222 offset:49280
	ds_read_b128 v[6:9], v222 offset:49312
	s_lshl_b64 s[0:1], s[26:27], 11
	s_add_u32 s0, s66, s0
	s_addc_u32 s1, s67, s1
	s_waitcnt lgkmcnt(1)
	v_rcp_f32_e32 v10, v2
	v_rcp_f32_e32 v11, v3
	s_lshl_b32 s2, s28, 1
	v_lshlrev_b32_e32 v0, 1, v0
	v_lshlrev_b32_e32 v34, 1, v215
	s_add_u32 s0, s0, s2
	v_add3_u32 v0, s46, v0, v34
	v_mul_f32_e32 v34, v48, v10
	v_mul_f32_e32 v10, v64, v10
	v_cvt_pk_bf16_f32 v10, v10, s0
	v_rcp_f32_e32 v12, v4
	ds_write_b16 v0, v10 offset:51264
	v_mul_f32_e32 v10, v49, v11
	v_cvt_pk_bf16_f32 v10, v10, s0
	ds_write_b16 v0, v10 offset:51328
	v_mul_f32_e32 v10, v65, v11
	v_cvt_pk_bf16_f32 v10, v10, s0
	v_rcp_f32_e32 v13, v5
	ds_write_b16 v0, v10 offset:51392
	v_mul_f32_e32 v10, v50, v12
	v_cvt_pk_bf16_f32 v10, v10, s0
	ds_write_b16 v0, v10 offset:51456
	v_mul_f32_e32 v10, v66, v12
	v_cvt_pk_bf16_f32 v10, v10, s0
	s_waitcnt lgkmcnt(4)
	v_rcp_f32_e32 v14, v6
	ds_write_b16 v0, v10 offset:51520
	v_mul_f32_e32 v10, v51, v13
	v_cvt_pk_bf16_f32 v10, v10, s0
	ds_write_b16 v0, v10 offset:51584
	v_mul_f32_e32 v10, v67, v13
	v_cvt_pk_bf16_f32 v10, v10, s0
	v_rcp_f32_e32 v15, v7
	ds_write_b16 v0, v10 offset:51648
	v_mul_f32_e32 v10, v52, v14
	v_cvt_pk_bf16_f32 v10, v10, s0
	ds_write_b16 v0, v10 offset:52224
	v_mul_f32_e32 v10, v68, v14
	v_cvt_pk_bf16_f32 v10, v10, s0
	v_rcp_f32_e32 v32, v8
	ds_write_b16 v0, v10 offset:52288
	v_mul_f32_e32 v10, v53, v15
	v_cvt_pk_bf16_f32 v10, v10, s0
	ds_write_b16 v0, v10 offset:52352
	v_mul_f32_e32 v10, v69, v15
	ds_read_b128 v[2:5], v222 offset:49344
	v_cvt_pk_bf16_f32 v10, v10, s0
	v_rcp_f32_e32 v33, v9
	ds_write_b16 v0, v10 offset:52416
	v_mul_f32_e32 v10, v54, v32
	v_cvt_pk_bf16_f32 v10, v10, s0
	ds_write_b16 v0, v10 offset:52480
	v_mul_f32_e32 v10, v70, v32
	v_cvt_pk_bf16_f32 v10, v10, s0
	ds_read_b128 v[6:9], v222 offset:49376
	s_waitcnt lgkmcnt(3)
	v_rcp_f32_e32 v2, v2
	ds_write_b16 v0, v10 offset:52544
	v_mul_f32_e32 v10, v55, v33
	v_cvt_pk_bf16_f32 v10, v10, s0
	v_rcp_f32_e32 v3, v3
	ds_write_b16 v0, v10 offset:52608
	v_mul_f32_e32 v10, v71, v33
	v_cvt_pk_bf16_f32 v10, v10, s0
	ds_write_b16 v0, v10 offset:52672
	v_mul_f32_e32 v10, v56, v2
	v_mul_f32_e32 v2, v72, v2
	v_cvt_pk_bf16_f32 v2, v2, s0
	v_rcp_f32_e32 v4, v4
	ds_write_b16 v0, v2 offset:53312
	v_mul_f32_e32 v2, v57, v3
	v_cvt_pk_bf16_f32 v2, v2, s0
	ds_write_b16 v0, v2 offset:53376
	v_mul_f32_e32 v2, v73, v3
	v_cvt_pk_bf16_f32 v2, v2, s0
	v_rcp_f32_e32 v5, v5
	ds_write_b16 v0, v2 offset:53440
	v_mul_f32_e32 v2, v58, v4
	v_cvt_pk_bf16_f32 v2, v2, s0
	ds_write_b16 v0, v2 offset:53504
	v_mul_f32_e32 v2, v74, v4
	v_cvt_pk_bf16_f32 v2, v2, s0
	s_waitcnt lgkmcnt(7)
	v_rcp_f32_e32 v6, v6
	ds_write_b16 v0, v2 offset:53568
	v_mul_f32_e32 v2, v59, v5
	v_cvt_pk_bf16_f32 v2, v2, s0
	ds_write_b16 v0, v2 offset:53632
	v_mul_f32_e32 v2, v75, v5
	v_cvt_pk_bf16_f32 v2, v2, s0
	v_rcp_f32_e32 v7, v7
	ds_write_b16 v0, v2 offset:53696
	v_mul_f32_e32 v2, v60, v6
	v_cvt_pk_bf16_f32 v2, v2, s0
	ds_write_b16 v0, v2 offset:54272
	v_mul_f32_e32 v2, v76, v6
	v_cvt_pk_bf16_f32 v2, v2, s0
	v_rcp_f32_e32 v8, v8
	ds_write_b16 v0, v2 offset:54336
	v_mul_f32_e32 v2, v61, v7
	v_cvt_pk_bf16_f32 v2, v2, s0
	ds_write_b16 v0, v2 offset:54400
	v_mul_f32_e32 v2, v77, v7
	v_cvt_pk_bf16_f32 v2, v2, s0
	v_rcp_f32_e32 v9, v9
	ds_write_b16 v0, v2 offset:54464
	v_mul_f32_e32 v2, v62, v8
	v_cvt_pk_bf16_f32 v2, v2, s0
	ds_write_b16 v0, v2 offset:54528
	v_mul_f32_e32 v2, v78, v8
	v_cvt_pk_bf16_f32 v2, v2, s0
	ds_write_b16 v0, v2 offset:54592
	v_mul_f32_e32 v2, v63, v9
	v_cvt_pk_bf16_f32 v2, v2, s0
	ds_write_b16 v0, v2 offset:54656
	v_mul_f32_e32 v2, v79, v9
	v_cvt_pk_bf16_f32 v34, v34, s0
	v_cvt_pk_bf16_f32 v10, v10, s0
	v_cvt_pk_bf16_f32 v2, v2, s0
	s_addc_u32 s1, s1, 0
	s_lshl_b64 s[2:3], s[30:31], 11
	ds_write_b16 v0, v34 offset:51200
	ds_write_b16 v0, v10 offset:53248
	ds_write_b16 v0, v2 offset:54720
	v_lshlrev_b32_e32 v0, 1, v214
	s_add_u32 s0, s0, s2
	v_and_b32_e32 v0, 0x70, v0
	s_addc_u32 s1, s1, s3
	v_lshrrev_b32_e32 v14, 3, v46
	v_add_u32_e32 v15, s46, v0
	s_waitcnt lgkmcnt(0)
	v_lshl_add_u64 v[10:11], s[0:1], 0, v[0:1]
	v_lshl_add_u32 v0, v14, 7, v15
	v_or_b32_e32 v32, 8, v14
	ds_read_b128 v[2:5], v0 offset:51200
	v_lshl_add_u32 v6, v32, 7, v15
	ds_read_b128 v[6:9], v6 offset:51200
	v_lshlrev_b32_e32 v0, 11, v14
	v_lshl_add_u64 v[12:13], v[10:11], 0, v[0:1]
	v_lshlrev_b32_e32 v0, 11, v32
	s_waitcnt lgkmcnt(1)
	global_store_dwordx4 v[12:13], v[2:5], off sc1
	s_nop 1
	v_lshl_add_u64 v[2:3], v[10:11], 0, v[0:1]
	v_or_b32_e32 v0, 16, v14
	s_waitcnt lgkmcnt(0)
	global_store_dwordx4 v[2:3], v[6:9], off sc1
	v_lshl_add_u32 v2, v0, 7, v15
	v_or_b32_e32 v14, 24, v14
	ds_read_b128 v[2:5], v2 offset:51200
	v_lshl_add_u32 v6, v14, 7, v15
	ds_read_b128 v[6:9], v6 offset:51200
	v_lshlrev_b32_e32 v0, 11, v0
	v_lshl_add_u64 v[12:13], v[10:11], 0, v[0:1]
	v_lshlrev_b32_e32 v0, 11, v14
	s_waitcnt lgkmcnt(1)
	global_store_dwordx4 v[12:13], v[2:5], off sc1
	s_nop 1
	v_lshl_add_u64 v[2:3], v[10:11], 0, v[0:1]
	s_waitcnt lgkmcnt(0)
	global_store_dwordx4 v[2:3], v[6:9], off sc1
	s_waitcnt lgkmcnt(0)
	s_barrier

; __device__ __forceinline__ unsigned cvtpk_s(float lo,float hi){f32x2_t v={lo,hi};bf16x2_t b=__builtin_convertvector(v,bf16x2_t);return __builtin_bit_cast(unsigned,b);}
;     ...
;     if(emode>=2){
;       #pragma unroll
;       for(int r=0;r<16;++r){
;         #pragma unroll
;         for(int d0=0;d0<2;++d0){ const float old=__uint_as_float((unsigned)stl[cr0(r)*64+d0*32]<<16); stl[cr0(r)*64+d0*32]=(bf16)(cvtpk_s(old-lam*(o[d0][r]*rli[r]),0.f)&0xffffu);} }
.Lfd_epi1:
	v_mov_b32_e32 v253, v252
	global_load_dwordx4 v[176:179], v253, s[86:87]
	v_add_u32_e32 v253, 0x2000, v253
	global_load_dwordx4 v[180:183], v253, s[86:87]
	v_add_u32_e32 v253, 0x2000, v253
	global_load_dwordx4 v[184:187], v253, s[86:87]
	v_add_u32_e32 v253, 0x2000, v253
	global_load_dwordx4 v[188:191], v253, s[86:87]
	v_add_u32_e32 v253, 0x2000, v253
	global_load_dwordx4 v[192:195], v253, s[86:87]
	v_add_u32_e32 v253, 0x2000, v253
	global_load_dwordx4 v[196:199], v253, s[86:87]
	v_add_u32_e32 v253, 0x2000, v253
	global_load_dwordx4 v[200:203], v253, s[86:87]
	v_add_u32_e32 v253, 0x2000, v253
	global_load_dwordx4 v[204:207], v253, s[86:87]
	s_waitcnt vmcnt(0)
	ds_write_b128 v219, v[176:179] offset:0
	ds_write_b128 v219, v[180:183] offset:1024
	ds_write_b128 v219, v[184:187] offset:2048
	ds_write_b128 v219, v[188:191] offset:3072
	ds_write_b128 v219, v[192:195] offset:4096
	ds_write_b128 v219, v[196:199] offset:5120
	ds_write_b128 v219, v[200:203] offset:6144
	ds_write_b128 v219, v[204:207] offset:7168
	s_waitcnt lgkmcnt(0)
	ds_read_u16 v128, v46 offset:0
	ds_read_u16 v129, v46 offset:256
	ds_read_u16 v130, v46 offset:512
	ds_read_u16 v131, v46 offset:768
	ds_read_u16 v132, v46 offset:2048
	ds_read_u16 v133, v46 offset:2304
	ds_read_u16 v134, v46 offset:2560
	ds_read_u16 v135, v46 offset:2816
	ds_read_u16 v136, v46 offset:4096
	ds_read_u16 v137, v46 offset:4352
	ds_read_u16 v138, v46 offset:4608
	ds_read_u16 v139, v46 offset:4864
	ds_read_u16 v140, v46 offset:6144
	ds_read_u16 v141, v46 offset:6400
	ds_read_u16 v142, v46 offset:6656
	ds_read_u16 v143, v46 offset:6912
	s_waitcnt lgkmcnt(0)
	v_mul_f32_e32 v4, v48, v112
	v_lshlrev_b32_e32 v5, 16, v128
	v_fma_f32 v4, -v216, v4, v5
	v_cvt_pk_bf16_f32 v4, v4, v4
	ds_write_b16 v46, v4 offset:0
	v_mul_f32_e32 v4, v49, v113
	v_lshlrev_b32_e32 v5, 16, v129
	v_fma_f32 v4, -v216, v4, v5
	v_cvt_pk_bf16_f32 v4, v4, v4
	ds_write_b16 v46, v4 offset:256
	v_mul_f32_e32 v4, v50, v114
	v_lshlrev_b32_e32 v5, 16, v130
	v_fma_f32 v4, -v216, v4, v5
	v_cvt_pk_bf16_f32 v4, v4, v4
	ds_write_b16 v46, v4 offset:512
	v_mul_f32_e32 v4, v51, v115
	v_lshlrev_b32_e32 v5, 16, v131
	v_fma_f32 v4, -v216, v4, v5
	v_cvt_pk_bf16_f32 v4, v4, v4
	ds_write_b16 v46, v4 offset:768
	v_mul_f32_e32 v4, v52, v116
	v_lshlrev_b32_e32 v5, 16, v132
	v_fma_f32 v4, -v216, v4, v5
	v_cvt_pk_bf16_f32 v4, v4, v4
	ds_write_b16 v46, v4 offset:2048
	v_mul_f32_e32 v4, v53, v117
	v_lshlrev_b32_e32 v5, 16, v133
	v_fma_f32 v4, -v216, v4, v5
	v_cvt_pk_bf16_f32 v4, v4, v4
	ds_write_b16 v46, v4 offset:2304
	v_mul_f32_e32 v4, v54, v118
	v_lshlrev_b32_e32 v5, 16, v134
	v_fma_f32 v4, -v216, v4, v5
	v_cvt_pk_bf16_f32 v4, v4, v4
	ds_write_b16 v46, v4 offset:2560
	v_mul_f32_e32 v4, v55, v119
	v_lshlrev_b32_e32 v5, 16, v135
	v_fma_f32 v4, -v216, v4, v5
	v_cvt_pk_bf16_f32 v4, v4, v4
	ds_write_b16 v46, v4 offset:2816
	v_mul_f32_e32 v4, v56, v120
	v_lshlrev_b32_e32 v5, 16, v136
	v_fma_f32 v4, -v216, v4, v5
	v_cvt_pk_bf16_f32 v4, v4, v4
	ds_write_b16 v46, v4 offset:4096
	v_mul_f32_e32 v4, v57, v121
	v_lshlrev_b32_e32 v5, 16, v137
	v_fma_f32 v4, -v216, v4, v5
	v_cvt_pk_bf16_f32 v4, v4, v4
	ds_write_b16 v46, v4 offset:4352
	v_mul_f32_e32 v4, v58, v122
	v_lshlrev_b32_e32 v5, 16, v138
	v_fma_f32 v4, -v216, v4, v5
	v_cvt_pk_bf16_f32 v4, v4, v4
	ds_write_b16 v46, v4 offset:4608
	v_mul_f32_e32 v4, v59, v123
	v_lshlrev_b32_e32 v5, 16, v139
	v_fma_f32 v4, -v216, v4, v5
	v_cvt_pk_bf16_f32 v4, v4, v4
	ds_write_b16 v46, v4 offset:4864
	v_mul_f32_e32 v4, v60, v124
	v_lshlrev_b32_e32 v5, 16, v140
	v_fma_f32 v4, -v216, v4, v5
	v_cvt_pk_bf16_f32 v4, v4, v4
	ds_write_b16 v46, v4 offset:6144
	v_mul_f32_e32 v4, v61, v125
	v_lshlrev_b32_e32 v5, 16, v141
	v_fma_f32 v4, -v216, v4, v5
	v_cvt_pk_bf16_f32 v4, v4, v4
	ds_write_b16 v46, v4 offset:6400
	v_mul_f32_e32 v4, v62, v126
	v_lshlrev_b32_e32 v5, 16, v142
	v_fma_f32 v4, -v216, v4, v5
	v_cvt_pk_bf16_f32 v4, v4, v4
	ds_write_b16 v46, v4 offset:6656
	v_mul_f32_e32 v4, v63, v127
	v_lshlrev_b32_e32 v5, 16, v143
	v_fma_f32 v4, -v216, v4, v5
	v_cvt_pk_bf16_f32 v4, v4, v4
	ds_write_b16 v46, v4 offset:6912
	ds_read_u16 v128, v46 offset:64
	ds_read_u16 v129, v46 offset:320
	ds_read_u16 v130, v46 offset:576
	ds_read_u16 v131, v46 offset:832
	ds_read_u16 v132, v46 offset:2112
	ds_read_u16 v133, v46 offset:2368
	ds_read_u16 v134, v46 offset:2624
	ds_read_u16 v135, v46 offset:2880
	ds_read_u16 v136, v46 offset:4160
	ds_read_u16 v137, v46 offset:4416
	ds_read_u16 v138, v46 offset:4672
	ds_read_u16 v139, v46 offset:4928
	ds_read_u16 v140, v46 offset:6208
	ds_read_u16 v141, v46 offset:6464
	ds_read_u16 v142, v46 offset:6720
	ds_read_u16 v143, v46 offset:6976
	s_waitcnt lgkmcnt(0)
; __device__ __forceinline__ unsigned cvtpk_s(float lo,float hi){f32x2_t v={lo,hi};bf16x2_t b=__builtin_convertvector(v,bf16x2_t);return __builtin_bit_cast(unsigned,b);}
;     ...
;     if(emode>=2){
;       #pragma unroll
;       for(int r=0;r<16;++r){
;         #pragma unroll
;         for(int d0=0;d0<2;++d0){ const float old=__uint_as_float((unsigned)stl[cr0(r)*64+d0*32]<<16); stl[cr0(r)*64+d0*32]=(bf16)(cvtpk_s(old-lam*(o[d0][r]*rli[r]),0.f)&0xffffu);} }
	v_mul_f32_e32 v4, v64, v112
	v_lshlrev_b32_e32 v5, 16, v128
	v_fma_f32 v4, -v216, v4, v5
	v_cvt_pk_bf16_f32 v4, v4, v4
	ds_write_b16 v46, v4 offset:64
	v_mul_f32_e32 v4, v65, v113
	v_lshlrev_b32_e32 v5, 16, v129
	v_fma_f32 v4, -v216, v4, v5
	v_cvt_pk_bf16_f32 v4, v4, v4
	ds_write_b16 v46, v4 offset:320
	v_mul_f32_e32 v4, v66, v114
	v_lshlrev_b32_e32 v5, 16, v130
	v_fma_f32 v4, -v216, v4, v5
	v_cvt_pk_bf16_f32 v4, v4, v4
	ds_write_b16 v46, v4 offset:576
	v_mul_f32_e32 v4, v67, v115
	v_lshlrev_b32_e32 v5, 16, v131
	v_fma_f32 v4, -v216, v4, v5
	v_cvt_pk_bf16_f32 v4, v4, v4
	ds_write_b16 v46, v4 offset:832
	v_mul_f32_e32 v4, v68, v116
	v_lshlrev_b32_e32 v5, 16, v132
	v_fma_f32 v4, -v216, v4, v5
	v_cvt_pk_bf16_f32 v4, v4, v4
	ds_write_b16 v46, v4 offset:2112
	v_mul_f32_e32 v4, v69, v117
	v_lshlrev_b32_e32 v5, 16, v133
	v_fma_f32 v4, -v216, v4, v5
	v_cvt_pk_bf16_f32 v4, v4, v4
	ds_write_b16 v46, v4 offset:2368
	v_mul_f32_e32 v4, v70, v118
	v_lshlrev_b32_e32 v5, 16, v134
	v_fma_f32 v4, -v216, v4, v5
	v_cvt_pk_bf16_f32 v4, v4, v4
	ds_write_b16 v46, v4 offset:2624
	v_mul_f32_e32 v4, v71, v119
	v_lshlrev_b32_e32 v5, 16, v135
	v_fma_f32 v4, -v216, v4, v5
	v_cvt_pk_bf16_f32 v4, v4, v4
	ds_write_b16 v46, v4 offset:2880
	v_mul_f32_e32 v4, v72, v120
	v_lshlrev_b32_e32 v5, 16, v136
	v_fma_f32 v4, -v216, v4, v5
	v_cvt_pk_bf16_f32 v4, v4, v4
	ds_write_b16 v46, v4 offset:4160
	v_mul_f32_e32 v4, v73, v121
	v_lshlrev_b32_e32 v5, 16, v137
	v_fma_f32 v4, -v216, v4, v5
	v_cvt_pk_bf16_f32 v4, v4, v4
	ds_write_b16 v46, v4 offset:4416
	v_mul_f32_e32 v4, v74, v122
	v_lshlrev_b32_e32 v5, 16, v138
	v_fma_f32 v4, -v216, v4, v5
	v_cvt_pk_bf16_f32 v4, v4, v4
	ds_write_b16 v46, v4 offset:4672
	v_mul_f32_e32 v4, v75, v123
	v_lshlrev_b32_e32 v5, 16, v139
	v_fma_f32 v4, -v216, v4, v5
	v_cvt_pk_bf16_f32 v4, v4, v4
	ds_write_b16 v46, v4 offset:4928
	v_mul_f32_e32 v4, v76, v124
	v_lshlrev_b32_e32 v5, 16, v140
	v_fma_f32 v4, -v216, v4, v5
	v_cvt_pk_bf16_f32 v4, v4, v4
	ds_write_b16 v46, v4 offset:6208
	v_mul_f32_e32 v4, v77, v125
	v_lshlrev_b32_e32 v5, 16, v141
	v_fma_f32 v4, -v216, v4, v5
	v_cvt_pk_bf16_f32 v4, v4, v4
	ds_write_b16 v46, v4 offset:6464
	v_mul_f32_e32 v4, v78, v126
	v_lshlrev_b32_e32 v5, 16, v142
	v_fma_f32 v4, -v216, v4, v5
	v_cvt_pk_bf16_f32 v4, v4, v4
	ds_write_b16 v46, v4 offset:6720
	v_mul_f32_e32 v4, v79, v127
	v_lshlrev_b32_e32 v5, 16, v143
	v_fma_f32 v4, -v216, v4, v5
	v_cvt_pk_bf16_f32 v4, v4, v4
	ds_write_b16 v46, v4 offset:6976
	ds_read_u16 v128, v46 offset:128
	ds_read_u16 v129, v46 offset:384
	ds_read_u16 v130, v46 offset:640
	ds_read_u16 v131, v46 offset:896
	ds_read_u16 v132, v46 offset:2176
	ds_read_u16 v133, v46 offset:2432
	ds_read_u16 v134, v46 offset:2688
	ds_read_u16 v135, v46 offset:2944
	ds_read_u16 v136, v46 offset:4224
	ds_read_u16 v137, v46 offset:4480
	ds_read_u16 v138, v46 offset:4736
	ds_read_u16 v139, v46 offset:4992
	ds_read_u16 v140, v46 offset:6272
	ds_read_u16 v141, v46 offset:6528
	ds_read_u16 v142, v46 offset:6784
	ds_read_u16 v143, v46 offset:7040
	s_waitcnt lgkmcnt(0)
	v_mul_f32_e32 v4, v80, v112
	v_lshlrev_b32_e32 v5, 16, v128
	v_fma_f32 v4, -v216, v4, v5
	v_cvt_pk_bf16_f32 v4, v4, v4
	ds_write_b16 v46, v4 offset:128
	v_mul_f32_e32 v4, v81, v113
	v_lshlrev_b32_e32 v5, 16, v129
	v_fma_f32 v4, -v216, v4, v5
	v_cvt_pk_bf16_f32 v4, v4, v4
	ds_write_b16 v46, v4 offset:384
	v_mul_f32_e32 v4, v82, v114
	v_lshlrev_b32_e32 v5, 16, v130
	v_fma_f32 v4, -v216, v4, v5
	v_cvt_pk_bf16_f32 v4, v4, v4
	ds_write_b16 v46, v4 offset:640
	v_mul_f32_e32 v4, v83, v115
	v_lshlrev_b32_e32 v5, 16, v131
	v_fma_f32 v4, -v216, v4, v5
	v_cvt_pk_bf16_f32 v4, v4, v4
	ds_write_b16 v46, v4 offset:896
	v_mul_f32_e32 v4, v84, v116
	v_lshlrev_b32_e32 v5, 16, v132
	v_fma_f32 v4, -v216, v4, v5
	v_cvt_pk_bf16_f32 v4, v4, v4
	ds_write_b16 v46, v4 offset:2176
	v_mul_f32_e32 v4, v85, v117
	v_lshlrev_b32_e32 v5, 16, v133
	v_fma_f32 v4, -v216, v4, v5
	v_cvt_pk_bf16_f32 v4, v4, v4
	ds_write_b16 v46, v4 offset:2432
	v_mul_f32_e32 v4, v86, v118
	v_lshlrev_b32_e32 v5, 16, v134
	v_fma_f32 v4, -v216, v4, v5
	v_cvt_pk_bf16_f32 v4, v4, v4
	ds_write_b16 v46, v4 offset:2688
	v_mul_f32_e32 v4, v87, v119
	v_lshlrev_b32_e32 v5, 16, v135
	v_fma_f32 v4, -v216, v4, v5
	v_cvt_pk_bf16_f32 v4, v4, v4
	ds_write_b16 v46, v4 offset:2944
	v_mul_f32_e32 v4, v88, v120
	v_lshlrev_b32_e32 v5, 16, v136
	v_fma_f32 v4, -v216, v4, v5
	v_cvt_pk_bf16_f32 v4, v4, v4
	ds_write_b16 v46, v4 offset:4224
	v_mul_f32_e32 v4, v89, v121
	v_lshlrev_b32_e32 v5, 16, v137
	v_fma_f32 v4, -v216, v4, v5
	v_cvt_pk_bf16_f32 v4, v4, v4
	ds_write_b16 v46, v4 offset:4480
	v_mul_f32_e32 v4, v90, v122
	v_lshlrev_b32_e32 v5, 16, v138
	v_fma_f32 v4, -v216, v4, v5
	v_cvt_pk_bf16_f32 v4, v4, v4
	ds_write_b16 v46, v4 offset:4736
	v_mul_f32_e32 v4, v91, v123
	v_lshlrev_b32_e32 v5, 16, v139
	v_fma_f32 v4, -v216, v4, v5
	v_cvt_pk_bf16_f32 v4, v4, v4
	ds_write_b16 v46, v4 offset:4992
	v_mul_f32_e32 v4, v92, v124
	v_lshlrev_b32_e32 v5, 16, v140
	v_fma_f32 v4, -v216, v4, v5
	v_cvt_pk_bf16_f32 v4, v4, v4
	ds_write_b16 v46, v4 offset:6272
	v_mul_f32_e32 v4, v93, v125
	v_lshlrev_b32_e32 v5, 16, v141
	v_fma_f32 v4, -v216, v4, v5
	v_cvt_pk_bf16_f32 v4, v4, v4
	ds_write_b16 v46, v4 offset:6528
	v_mul_f32_e32 v4, v94, v126
	v_lshlrev_b32_e32 v5, 16, v142
	v_fma_f32 v4, -v216, v4, v5
	v_cvt_pk_bf16_f32 v4, v4, v4
	ds_write_b16 v46, v4 offset:6784
	v_mul_f32_e32 v4, v95, v127
	v_lshlrev_b32_e32 v5, 16, v143
	v_fma_f32 v4, -v216, v4, v5
	v_cvt_pk_bf16_f32 v4, v4, v4
	ds_write_b16 v46, v4 offset:7040
	ds_read_u16 v128, v46 offset:192
	ds_read_u16 v129, v46 offset:448
	ds_read_u16 v130, v46 offset:704
	ds_read_u16 v131, v46 offset:960
	ds_read_u16 v132, v46 offset:2240
	ds_read_u16 v133, v46 offset:2496
	ds_read_u16 v134, v46 offset:2752
	ds_read_u16 v135, v46 offset:3008
	ds_read_u16 v136, v46 offset:4288
	ds_read_u16 v137, v46 offset:4544
	ds_read_u16 v138, v46 offset:4800
	ds_read_u16 v139, v46 offset:5056
	ds_read_u16 v140, v46 offset:6336
	ds_read_u16 v141, v46 offset:6592
	ds_read_u16 v142, v46 offset:6848
	ds_read_u16 v143, v46 offset:7104
	s_waitcnt lgkmcnt(0)
; __device__ __forceinline__ unsigned cvtpk_s(float lo,float hi){f32x2_t v={lo,hi};bf16x2_t b=__builtin_convertvector(v,bf16x2_t);return __builtin_bit_cast(unsigned,b);}
; #define ATTN_STORE16(p,v) st16_wt((p),(v))
;     ...
;     if(emode>=2){
;       #pragma unroll
;       for(int r=0;r<16;++r){
;         #pragma unroll
;         for(int d0=0;d0<2;++d0){ const float old=__uint_as_float((unsigned)stl[cr0(r)*64+d0*32]<<16); stl[cr0(r)*64+d0*32]=(bf16)(cvtpk_s(old-lam*(o[d0][r]*rli[r]),0.f)&0xffffu);} }
;     ...
;     } else if(emode==3){
;       #pragma unroll
;       for(int i=0;i<4;++i){const int row=i*8+(lane>>3),ch=lane&7;
;         const u32x4 v0=*(const u32x4*)(stg+row*64+ch*8), v1=*(const u32x4*)(stg+2048+row*64+ch*8);
;         float f[16]; float ss=0.f;
;         #pragma unroll
;         for(int j=0;j<4;++j){ f[2*j]=__uint_as_float(v0[j]<<16); f[2*j+1]=__uint_as_float(v0[j]&0xffff0000u); f[8+2*j]=__uint_as_float(v1[j]<<16); f[8+2*j+1]=__uint_as_float(v1[j]&0xffff0000u); }
;         #pragma unroll
;         for(int j=0;j<16;++j)ss+=f[j]*f[j];
;         ss+=__shfl_xor(ss,1); ss+=__shfl_xor(ss,2); ss+=__shfl_xor(ss,4);
;         const float rn=__builtin_amdgcn_rsqf(ss*(1.f/128.f)+1e-6f)*0.8f;
;         u32x4 w0,w1;
;         #pragma unroll
;         for(int j=0;j<4;++j){ w0[j]=cvtpk_s(f[2*j]*rn,f[2*j+1]*rn); w1[j]=cvtpk_s(f[8+2*j]*rn,f[8+2*j+1]*rn); }
;         ATTN_STORE16(Ow+(long)row*OP+ch*8,w0); ATTN_STORE16(Ow+(long)row*OP+64+ch*8,w1);}
	v_mul_f32_e32 v4, v96, v112
	v_lshlrev_b32_e32 v5, 16, v128
	v_fma_f32 v4, -v216, v4, v5
	v_cvt_pk_bf16_f32 v4, v4, v4
	ds_write_b16 v46, v4 offset:192
	v_mul_f32_e32 v4, v97, v113
	v_lshlrev_b32_e32 v5, 16, v129
	v_fma_f32 v4, -v216, v4, v5
	v_cvt_pk_bf16_f32 v4, v4, v4
	ds_write_b16 v46, v4 offset:448
	v_mul_f32_e32 v4, v98, v114
	v_lshlrev_b32_e32 v5, 16, v130
	v_fma_f32 v4, -v216, v4, v5
	v_cvt_pk_bf16_f32 v4, v4, v4
	ds_write_b16 v46, v4 offset:704
	v_mul_f32_e32 v4, v99, v115
	v_lshlrev_b32_e32 v5, 16, v131
	v_fma_f32 v4, -v216, v4, v5
	v_cvt_pk_bf16_f32 v4, v4, v4
	ds_write_b16 v46, v4 offset:960
	v_mul_f32_e32 v4, v100, v116
	v_lshlrev_b32_e32 v5, 16, v132
	v_fma_f32 v4, -v216, v4, v5
	v_cvt_pk_bf16_f32 v4, v4, v4
	ds_write_b16 v46, v4 offset:2240
	v_mul_f32_e32 v4, v101, v117
	v_lshlrev_b32_e32 v5, 16, v133
	v_fma_f32 v4, -v216, v4, v5
	v_cvt_pk_bf16_f32 v4, v4, v4
	ds_write_b16 v46, v4 offset:2496
	v_mul_f32_e32 v4, v102, v118
	v_lshlrev_b32_e32 v5, 16, v134
	v_fma_f32 v4, -v216, v4, v5
	v_cvt_pk_bf16_f32 v4, v4, v4
	ds_write_b16 v46, v4 offset:2752
	v_mul_f32_e32 v4, v103, v119
	v_lshlrev_b32_e32 v5, 16, v135
	v_fma_f32 v4, -v216, v4, v5
	v_cvt_pk_bf16_f32 v4, v4, v4
	ds_write_b16 v46, v4 offset:3008
	v_mul_f32_e32 v4, v104, v120
	v_lshlrev_b32_e32 v5, 16, v136
	v_fma_f32 v4, -v216, v4, v5
	v_cvt_pk_bf16_f32 v4, v4, v4
	ds_write_b16 v46, v4 offset:4288
	v_mul_f32_e32 v4, v105, v121
	v_lshlrev_b32_e32 v5, 16, v137
	v_fma_f32 v4, -v216, v4, v5
	v_cvt_pk_bf16_f32 v4, v4, v4
	ds_write_b16 v46, v4 offset:4544
	v_mul_f32_e32 v4, v106, v122
	v_lshlrev_b32_e32 v5, 16, v138
	v_fma_f32 v4, -v216, v4, v5
	v_cvt_pk_bf16_f32 v4, v4, v4
	ds_write_b16 v46, v4 offset:4800
	v_mul_f32_e32 v4, v107, v123
	v_lshlrev_b32_e32 v5, 16, v139
	v_fma_f32 v4, -v216, v4, v5
	v_cvt_pk_bf16_f32 v4, v4, v4
	ds_write_b16 v46, v4 offset:5056
	v_mul_f32_e32 v4, v108, v124
	v_lshlrev_b32_e32 v5, 16, v140
	v_fma_f32 v4, -v216, v4, v5
	v_cvt_pk_bf16_f32 v4, v4, v4
	ds_write_b16 v46, v4 offset:6336
	v_mul_f32_e32 v4, v109, v125
	v_lshlrev_b32_e32 v5, 16, v141
	v_fma_f32 v4, -v216, v4, v5
	v_cvt_pk_bf16_f32 v4, v4, v4
	ds_write_b16 v46, v4 offset:6592
	v_mul_f32_e32 v4, v110, v126
	v_lshlrev_b32_e32 v5, 16, v142
	v_fma_f32 v4, -v216, v4, v5
	v_cvt_pk_bf16_f32 v4, v4, v4
	ds_write_b16 v46, v4 offset:6848
	v_mul_f32_e32 v4, v111, v127
	v_lshlrev_b32_e32 v5, 16, v143
	v_fma_f32 v4, -v216, v4, v5
	v_cvt_pk_bf16_f32 v4, v4, v4
	ds_write_b16 v46, v4 offset:7104
	s_waitcnt lgkmcnt(0)
	ds_read_b128 v[176:179], v219 offset:0
	ds_read_b128 v[180:183], v219 offset:1024
	ds_read_b128 v[184:187], v219 offset:2048
	ds_read_b128 v[188:191], v219 offset:3072
	ds_read_b128 v[192:195], v219 offset:4096
	ds_read_b128 v[196:199], v219 offset:5120
	ds_read_b128 v[200:203], v219 offset:6144
	ds_read_b128 v[204:207], v219 offset:7168
	s_waitcnt lgkmcnt(0)
	v_mov_b32_e32 v37, 0x3c000000
	v_mov_b32_e32 v38, 0x358637bd
	v_lshlrev_b32_e32 v112, 16, v176
	v_and_b32_e32 v113, 0xffff0000, v176
	v_lshlrev_b32_e32 v114, 16, v177
	v_and_b32_e32 v115, 0xffff0000, v177
	v_lshlrev_b32_e32 v116, 16, v178
	v_and_b32_e32 v117, 0xffff0000, v178
	v_lshlrev_b32_e32 v118, 16, v179
	v_and_b32_e32 v119, 0xffff0000, v179
	v_mul_f32_e32 v4, v112, v112
	v_fmac_f32_e32 v4, v113, v113
	v_fmac_f32_e32 v4, v114, v114
	v_fmac_f32_e32 v4, v115, v115
	v_fmac_f32_e32 v4, v116, v116
	v_fmac_f32_e32 v4, v117, v117
	v_fmac_f32_e32 v4, v118, v118
	v_fmac_f32_e32 v4, v119, v119
	s_nop 1
	v_mov_b32_dpp v5, v4 row_ror:8 row_mask:0xf bank_mask:0xf
	v_add_f32_e32 v4, v4, v5
	s_nop 1
	v_mov_b32_dpp v5, v4 row_ror:4 row_mask:0xf bank_mask:0xf
	v_add_f32_e32 v4, v4, v5
	s_nop 1
	v_mov_b32_dpp v5, v4 row_ror:2 row_mask:0xf bank_mask:0xf
	v_add_f32_e32 v4, v4, v5
	s_nop 1
	v_mov_b32_dpp v5, v4 row_ror:1 row_mask:0xf bank_mask:0xf
	v_add_f32_e32 v4, v4, v5
	v_fma_f32 v4, v4, v37, v38
	v_rsq_f32_e32 v4, v4
	s_nop 0
	v_mul_f32_e32 v4, 0x3f4ccccd, v4
	v_mul_f32_e32 v112, v112, v4
	v_mul_f32_e32 v113, v113, v4
	v_mul_f32_e32 v114, v114, v4
	v_mul_f32_e32 v115, v115, v4
	v_mul_f32_e32 v116, v116, v4
	v_mul_f32_e32 v117, v117, v4
	v_mul_f32_e32 v118, v118, v4
	v_mul_f32_e32 v119, v119, v4
	v_cvt_pk_bf16_f32 v176, v112, v113
	v_cvt_pk_bf16_f32 v177, v114, v115
	v_cvt_pk_bf16_f32 v178, v116, v117
	v_cvt_pk_bf16_f32 v179, v118, v119
	v_mov_b32_e32 v253, v252
	global_store_dwordx4 v253, v[176:179], s[86:87] sc1
	v_lshlrev_b32_e32 v112, 16, v180
	v_and_b32_e32 v113, 0xffff0000, v180
	v_lshlrev_b32_e32 v114, 16, v181
	v_and_b32_e32 v115, 0xffff0000, v181
	v_lshlrev_b32_e32 v116, 16, v182
	v_and_b32_e32 v117, 0xffff0000, v182
	v_lshlrev_b32_e32 v118, 16, v183
	v_and_b32_e32 v119, 0xffff0000, v183
	v_mul_f32_e32 v4, v112, v112
	v_fmac_f32_e32 v4, v113, v113
	v_fmac_f32_e32 v4, v114, v114
	v_fmac_f32_e32 v4, v115, v115
	v_fmac_f32_e32 v4, v116, v116
	v_fmac_f32_e32 v4, v117, v117
	v_fmac_f32_e32 v4, v118, v118
	v_fmac_f32_e32 v4, v119, v119
	s_nop 1
	v_mov_b32_dpp v5, v4 row_ror:8 row_mask:0xf bank_mask:0xf
	v_add_f32_e32 v4, v4, v5
	s_nop 1
	v_mov_b32_dpp v5, v4 row_ror:4 row_mask:0xf bank_mask:0xf
	v_add_f32_e32 v4, v4, v5
	s_nop 1
	v_mov_b32_dpp v5, v4 row_ror:2 row_mask:0xf bank_mask:0xf
	v_add_f32_e32 v4, v4, v5
	s_nop 1
	v_mov_b32_dpp v5, v4 row_ror:1 row_mask:0xf bank_mask:0xf
	v_add_f32_e32 v4, v4, v5
	v_fma_f32 v4, v4, v37, v38
	v_rsq_f32_e32 v4, v4
	s_nop 0
	v_mul_f32_e32 v4, 0x3f4ccccd, v4
	v_mul_f32_e32 v112, v112, v4
	v_mul_f32_e32 v113, v113, v4
	v_mul_f32_e32 v114, v114, v4
	v_mul_f32_e32 v115, v115, v4
	v_mul_f32_e32 v116, v116, v4
	v_mul_f32_e32 v117, v117, v4
	v_mul_f32_e32 v118, v118, v4
	v_mul_f32_e32 v119, v119, v4
; __device__ __forceinline__ unsigned cvtpk_s(float lo,float hi){f32x2_t v={lo,hi};bf16x2_t b=__builtin_convertvector(v,bf16x2_t);return __builtin_bit_cast(unsigned,b);}
; #define ATTN_STORE16(p,v) st16_wt((p),(v))
;     ...
;     } else if(emode==3){
;       #pragma unroll
;       for(int i=0;i<4;++i){const int row=i*8+(lane>>3),ch=lane&7;
;         const u32x4 v0=*(const u32x4*)(stg+row*64+ch*8), v1=*(const u32x4*)(stg+2048+row*64+ch*8);
;         float f[16]; float ss=0.f;
;         #pragma unroll
;         for(int j=0;j<4;++j){ f[2*j]=__uint_as_float(v0[j]<<16); f[2*j+1]=__uint_as_float(v0[j]&0xffff0000u); f[8+2*j]=__uint_as_float(v1[j]<<16); f[8+2*j+1]=__uint_as_float(v1[j]&0xffff0000u); }
;         #pragma unroll
;         for(int j=0;j<16;++j)ss+=f[j]*f[j];
;         ss+=__shfl_xor(ss,1); ss+=__shfl_xor(ss,2); ss+=__shfl_xor(ss,4);
;         const float rn=__builtin_amdgcn_rsqf(ss*(1.f/128.f)+1e-6f)*0.8f;
;         u32x4 w0,w1;
;         #pragma unroll
;         for(int j=0;j<4;++j){ w0[j]=cvtpk_s(f[2*j]*rn,f[2*j+1]*rn); w1[j]=cvtpk_s(f[8+2*j]*rn,f[8+2*j+1]*rn); }
;         ATTN_STORE16(Ow+(long)row*OP+ch*8,w0); ATTN_STORE16(Ow+(long)row*OP+64+ch*8,w1);}
	v_cvt_pk_bf16_f32 v180, v112, v113
	v_cvt_pk_bf16_f32 v181, v114, v115
	v_cvt_pk_bf16_f32 v182, v116, v117
	v_cvt_pk_bf16_f32 v183, v118, v119
	v_add_u32_e32 v253, 0x2000, v253
	global_store_dwordx4 v253, v[180:183], s[86:87] sc1
	v_lshlrev_b32_e32 v112, 16, v184
	v_and_b32_e32 v113, 0xffff0000, v184
	v_lshlrev_b32_e32 v114, 16, v185
	v_and_b32_e32 v115, 0xffff0000, v185
	v_lshlrev_b32_e32 v116, 16, v186
	v_and_b32_e32 v117, 0xffff0000, v186
	v_lshlrev_b32_e32 v118, 16, v187
	v_and_b32_e32 v119, 0xffff0000, v187
	v_mul_f32_e32 v4, v112, v112
	v_fmac_f32_e32 v4, v113, v113
	v_fmac_f32_e32 v4, v114, v114
	v_fmac_f32_e32 v4, v115, v115
	v_fmac_f32_e32 v4, v116, v116
	v_fmac_f32_e32 v4, v117, v117
	v_fmac_f32_e32 v4, v118, v118
	v_fmac_f32_e32 v4, v119, v119
	s_nop 1
	v_mov_b32_dpp v5, v4 row_ror:8 row_mask:0xf bank_mask:0xf
	v_add_f32_e32 v4, v4, v5
	s_nop 1
	v_mov_b32_dpp v5, v4 row_ror:4 row_mask:0xf bank_mask:0xf
	v_add_f32_e32 v4, v4, v5
	s_nop 1
	v_mov_b32_dpp v5, v4 row_ror:2 row_mask:0xf bank_mask:0xf
	v_add_f32_e32 v4, v4, v5
	s_nop 1
	v_mov_b32_dpp v5, v4 row_ror:1 row_mask:0xf bank_mask:0xf
	v_add_f32_e32 v4, v4, v5
	v_fma_f32 v4, v4, v37, v38
	v_rsq_f32_e32 v4, v4
	s_nop 0
	v_mul_f32_e32 v4, 0x3f4ccccd, v4
	v_mul_f32_e32 v112, v112, v4
	v_mul_f32_e32 v113, v113, v4
	v_mul_f32_e32 v114, v114, v4
	v_mul_f32_e32 v115, v115, v4
	v_mul_f32_e32 v116, v116, v4
	v_mul_f32_e32 v117, v117, v4
	v_mul_f32_e32 v118, v118, v4
	v_mul_f32_e32 v119, v119, v4
	v_cvt_pk_bf16_f32 v184, v112, v113
	v_cvt_pk_bf16_f32 v185, v114, v115
	v_cvt_pk_bf16_f32 v186, v116, v117
	v_cvt_pk_bf16_f32 v187, v118, v119
	v_add_u32_e32 v253, 0x2000, v253
	global_store_dwordx4 v253, v[184:187], s[86:87] sc1
	v_lshlrev_b32_e32 v112, 16, v188
	v_and_b32_e32 v113, 0xffff0000, v188
	v_lshlrev_b32_e32 v114, 16, v189
	v_and_b32_e32 v115, 0xffff0000, v189
	v_lshlrev_b32_e32 v116, 16, v190
	v_and_b32_e32 v117, 0xffff0000, v190
	v_lshlrev_b32_e32 v118, 16, v191
	v_and_b32_e32 v119, 0xffff0000, v191
	v_mul_f32_e32 v4, v112, v112
	v_fmac_f32_e32 v4, v113, v113
	v_fmac_f32_e32 v4, v114, v114
	v_fmac_f32_e32 v4, v115, v115
	v_fmac_f32_e32 v4, v116, v116
	v_fmac_f32_e32 v4, v117, v117
	v_fmac_f32_e32 v4, v118, v118
	v_fmac_f32_e32 v4, v119, v119
	s_nop 1
	v_mov_b32_dpp v5, v4 row_ror:8 row_mask:0xf bank_mask:0xf
	v_add_f32_e32 v4, v4, v5
	s_nop 1
	v_mov_b32_dpp v5, v4 row_ror:4 row_mask:0xf bank_mask:0xf
	v_add_f32_e32 v4, v4, v5
	s_nop 1
	v_mov_b32_dpp v5, v4 row_ror:2 row_mask:0xf bank_mask:0xf
	v_add_f32_e32 v4, v4, v5
	s_nop 1
	v_mov_b32_dpp v5, v4 row_ror:1 row_mask:0xf bank_mask:0xf
	v_add_f32_e32 v4, v4, v5
	v_fma_f32 v4, v4, v37, v38
	v_rsq_f32_e32 v4, v4
	s_nop 0
	v_mul_f32_e32 v4, 0x3f4ccccd, v4
	v_mul_f32_e32 v112, v112, v4
	v_mul_f32_e32 v113, v113, v4
	v_mul_f32_e32 v114, v114, v4
	v_mul_f32_e32 v115, v115, v4
	v_mul_f32_e32 v116, v116, v4
	v_mul_f32_e32 v117, v117, v4
	v_mul_f32_e32 v118, v118, v4
	v_mul_f32_e32 v119, v119, v4
	v_cvt_pk_bf16_f32 v188, v112, v113
	v_cvt_pk_bf16_f32 v189, v114, v115
	v_cvt_pk_bf16_f32 v190, v116, v117
	v_cvt_pk_bf16_f32 v191, v118, v119
	v_add_u32_e32 v253, 0x2000, v253
	global_store_dwordx4 v253, v[188:191], s[86:87] sc1
	v_lshlrev_b32_e32 v112, 16, v192
	v_and_b32_e32 v113, 0xffff0000, v192
	v_lshlrev_b32_e32 v114, 16, v193
	v_and_b32_e32 v115, 0xffff0000, v193
	v_lshlrev_b32_e32 v116, 16, v194
	v_and_b32_e32 v117, 0xffff0000, v194
	v_lshlrev_b32_e32 v118, 16, v195
	v_and_b32_e32 v119, 0xffff0000, v195
	v_mul_f32_e32 v4, v112, v112
	v_fmac_f32_e32 v4, v113, v113
	v_fmac_f32_e32 v4, v114, v114
	v_fmac_f32_e32 v4, v115, v115
	v_fmac_f32_e32 v4, v116, v116
	v_fmac_f32_e32 v4, v117, v117
	v_fmac_f32_e32 v4, v118, v118
	v_fmac_f32_e32 v4, v119, v119
	s_nop 1
	v_mov_b32_dpp v5, v4 row_ror:8 row_mask:0xf bank_mask:0xf
	v_add_f32_e32 v4, v4, v5
	s_nop 1
	v_mov_b32_dpp v5, v4 row_ror:4 row_mask:0xf bank_mask:0xf
	v_add_f32_e32 v4, v4, v5
	s_nop 1
	v_mov_b32_dpp v5, v4 row_ror:2 row_mask:0xf bank_mask:0xf
	v_add_f32_e32 v4, v4, v5
	s_nop 1
	v_mov_b32_dpp v5, v4 row_ror:1 row_mask:0xf bank_mask:0xf
	v_add_f32_e32 v4, v4, v5
	v_fma_f32 v4, v4, v37, v38
	v_rsq_f32_e32 v4, v4
	s_nop 0
	v_mul_f32_e32 v4, 0x3f4ccccd, v4
	v_mul_f32_e32 v112, v112, v4
	v_mul_f32_e32 v113, v113, v4
	v_mul_f32_e32 v114, v114, v4
	v_mul_f32_e32 v115, v115, v4
	v_mul_f32_e32 v116, v116, v4
	v_mul_f32_e32 v117, v117, v4
	v_mul_f32_e32 v118, v118, v4
	v_mul_f32_e32 v119, v119, v4
	v_cvt_pk_bf16_f32 v192, v112, v113
	v_cvt_pk_bf16_f32 v193, v114, v115
	v_cvt_pk_bf16_f32 v194, v116, v117
	v_cvt_pk_bf16_f32 v195, v118, v119
; __device__ __forceinline__ unsigned cvtpk_s(float lo,float hi){f32x2_t v={lo,hi};bf16x2_t b=__builtin_convertvector(v,bf16x2_t);return __builtin_bit_cast(unsigned,b);}
; #define ATTN_STORE16(p,v) st16_wt((p),(v))
;     ...
;     } else if(emode==3){
;       #pragma unroll
;       for(int i=0;i<4;++i){const int row=i*8+(lane>>3),ch=lane&7;
;         const u32x4 v0=*(const u32x4*)(stg+row*64+ch*8), v1=*(const u32x4*)(stg+2048+row*64+ch*8);
;         float f[16]; float ss=0.f;
;         #pragma unroll
;         for(int j=0;j<4;++j){ f[2*j]=__uint_as_float(v0[j]<<16); f[2*j+1]=__uint_as_float(v0[j]&0xffff0000u); f[8+2*j]=__uint_as_float(v1[j]<<16); f[8+2*j+1]=__uint_as_float(v1[j]&0xffff0000u); }
;         #pragma unroll
;         for(int j=0;j<16;++j)ss+=f[j]*f[j];
;         ss+=__shfl_xor(ss,1); ss+=__shfl_xor(ss,2); ss+=__shfl_xor(ss,4);
;         const float rn=__builtin_amdgcn_rsqf(ss*(1.f/128.f)+1e-6f)*0.8f;
;         u32x4 w0,w1;
;         #pragma unroll
;         for(int j=0;j<4;++j){ w0[j]=cvtpk_s(f[2*j]*rn,f[2*j+1]*rn); w1[j]=cvtpk_s(f[8+2*j]*rn,f[8+2*j+1]*rn); }
;         ATTN_STORE16(Ow+(long)row*OP+ch*8,w0); ATTN_STORE16(Ow+(long)row*OP+64+ch*8,w1);}
	v_add_u32_e32 v253, 0x2000, v253
	global_store_dwordx4 v253, v[192:195], s[86:87] sc1
	v_lshlrev_b32_e32 v112, 16, v196
	v_and_b32_e32 v113, 0xffff0000, v196
	v_lshlrev_b32_e32 v114, 16, v197
	v_and_b32_e32 v115, 0xffff0000, v197
	v_lshlrev_b32_e32 v116, 16, v198
	v_and_b32_e32 v117, 0xffff0000, v198
	v_lshlrev_b32_e32 v118, 16, v199
	v_and_b32_e32 v119, 0xffff0000, v199
	v_mul_f32_e32 v4, v112, v112
	v_fmac_f32_e32 v4, v113, v113
	v_fmac_f32_e32 v4, v114, v114
	v_fmac_f32_e32 v4, v115, v115
	v_fmac_f32_e32 v4, v116, v116
	v_fmac_f32_e32 v4, v117, v117
	v_fmac_f32_e32 v4, v118, v118
	v_fmac_f32_e32 v4, v119, v119
	s_nop 1
	v_mov_b32_dpp v5, v4 row_ror:8 row_mask:0xf bank_mask:0xf
	v_add_f32_e32 v4, v4, v5
	s_nop 1
	v_mov_b32_dpp v5, v4 row_ror:4 row_mask:0xf bank_mask:0xf
	v_add_f32_e32 v4, v4, v5
	s_nop 1
	v_mov_b32_dpp v5, v4 row_ror:2 row_mask:0xf bank_mask:0xf
	v_add_f32_e32 v4, v4, v5
	s_nop 1
	v_mov_b32_dpp v5, v4 row_ror:1 row_mask:0xf bank_mask:0xf
	v_add_f32_e32 v4, v4, v5
	v_fma_f32 v4, v4, v37, v38
	v_rsq_f32_e32 v4, v4
	s_nop 0
	v_mul_f32_e32 v4, 0x3f4ccccd, v4
	v_mul_f32_e32 v112, v112, v4
	v_mul_f32_e32 v113, v113, v4
	v_mul_f32_e32 v114, v114, v4
	v_mul_f32_e32 v115, v115, v4
	v_mul_f32_e32 v116, v116, v4
	v_mul_f32_e32 v117, v117, v4
	v_mul_f32_e32 v118, v118, v4
	v_mul_f32_e32 v119, v119, v4
	v_cvt_pk_bf16_f32 v196, v112, v113
	v_cvt_pk_bf16_f32 v197, v114, v115
	v_cvt_pk_bf16_f32 v198, v116, v117
	v_cvt_pk_bf16_f32 v199, v118, v119
	v_add_u32_e32 v253, 0x2000, v253
	global_store_dwordx4 v253, v[196:199], s[86:87] sc1
	v_lshlrev_b32_e32 v112, 16, v200
	v_and_b32_e32 v113, 0xffff0000, v200
	v_lshlrev_b32_e32 v114, 16, v201
	v_and_b32_e32 v115, 0xffff0000, v201
	v_lshlrev_b32_e32 v116, 16, v202
	v_and_b32_e32 v117, 0xffff0000, v202
	v_lshlrev_b32_e32 v118, 16, v203
	v_and_b32_e32 v119, 0xffff0000, v203
	v_mul_f32_e32 v4, v112, v112
	v_fmac_f32_e32 v4, v113, v113
	v_fmac_f32_e32 v4, v114, v114
	v_fmac_f32_e32 v4, v115, v115
	v_fmac_f32_e32 v4, v116, v116
	v_fmac_f32_e32 v4, v117, v117
	v_fmac_f32_e32 v4, v118, v118
	v_fmac_f32_e32 v4, v119, v119
	s_nop 1
	v_mov_b32_dpp v5, v4 row_ror:8 row_mask:0xf bank_mask:0xf
	v_add_f32_e32 v4, v4, v5
	s_nop 1
	v_mov_b32_dpp v5, v4 row_ror:4 row_mask:0xf bank_mask:0xf
	v_add_f32_e32 v4, v4, v5
	s_nop 1
	v_mov_b32_dpp v5, v4 row_ror:2 row_mask:0xf bank_mask:0xf
	v_add_f32_e32 v4, v4, v5
	s_nop 1
	v_mov_b32_dpp v5, v4 row_ror:1 row_mask:0xf bank_mask:0xf
	v_add_f32_e32 v4, v4, v5
	v_fma_f32 v4, v4, v37, v38
	v_rsq_f32_e32 v4, v4
	s_nop 0
	v_mul_f32_e32 v4, 0x3f4ccccd, v4
	v_mul_f32_e32 v112, v112, v4
	v_mul_f32_e32 v113, v113, v4
	v_mul_f32_e32 v114, v114, v4
	v_mul_f32_e32 v115, v115, v4
	v_mul_f32_e32 v116, v116, v4
	v_mul_f32_e32 v117, v117, v4
	v_mul_f32_e32 v118, v118, v4
	v_mul_f32_e32 v119, v119, v4
	v_cvt_pk_bf16_f32 v200, v112, v113
	v_cvt_pk_bf16_f32 v201, v114, v115
	v_cvt_pk_bf16_f32 v202, v116, v117
	v_cvt_pk_bf16_f32 v203, v118, v119
	v_add_u32_e32 v253, 0x2000, v253
	global_store_dwordx4 v253, v[200:203], s[86:87] sc1
	v_lshlrev_b32_e32 v112, 16, v204
	v_and_b32_e32 v113, 0xffff0000, v204
	v_lshlrev_b32_e32 v114, 16, v205
	v_and_b32_e32 v115, 0xffff0000, v205
	v_lshlrev_b32_e32 v116, 16, v206
	v_and_b32_e32 v117, 0xffff0000, v206
	v_lshlrev_b32_e32 v118, 16, v207
	v_and_b32_e32 v119, 0xffff0000, v207
	v_mul_f32_e32 v4, v112, v112
	v_fmac_f32_e32 v4, v113, v113
	v_fmac_f32_e32 v4, v114, v114
	v_fmac_f32_e32 v4, v115, v115
	v_fmac_f32_e32 v4, v116, v116
	v_fmac_f32_e32 v4, v117, v117
	v_fmac_f32_e32 v4, v118, v118
	v_fmac_f32_e32 v4, v119, v119
	s_nop 1
	v_mov_b32_dpp v5, v4 row_ror:8 row_mask:0xf bank_mask:0xf
	v_add_f32_e32 v4, v4, v5
	s_nop 1
	v_mov_b32_dpp v5, v4 row_ror:4 row_mask:0xf bank_mask:0xf
	v_add_f32_e32 v4, v4, v5
	s_nop 1
	v_mov_b32_dpp v5, v4 row_ror:2 row_mask:0xf bank_mask:0xf
	v_add_f32_e32 v4, v4, v5
	s_nop 1
	v_mov_b32_dpp v5, v4 row_ror:1 row_mask:0xf bank_mask:0xf
	v_add_f32_e32 v4, v4, v5
	v_fma_f32 v4, v4, v37, v38
	v_rsq_f32_e32 v4, v4
	s_nop 0
	v_mul_f32_e32 v4, 0x3f4ccccd, v4
	v_mul_f32_e32 v112, v112, v4
	v_mul_f32_e32 v113, v113, v4
	v_mul_f32_e32 v114, v114, v4
	v_mul_f32_e32 v115, v115, v4
	v_mul_f32_e32 v116, v116, v4
	v_mul_f32_e32 v117, v117, v4
	v_mul_f32_e32 v118, v118, v4
	v_mul_f32_e32 v119, v119, v4
	v_cvt_pk_bf16_f32 v204, v112, v113
	v_cvt_pk_bf16_f32 v205, v114, v115
	v_cvt_pk_bf16_f32 v206, v116, v117
	v_cvt_pk_bf16_f32 v207, v118, v119
	v_add_u32_e32 v253, 0x2000, v253
	global_store_dwordx4 v253, v[204:207], s[86:87] sc1
	s_waitcnt vmcnt(0) lgkmcnt(0)
	s_barrier
	s_branch .LBB0_1511
